# strategy: one static s_setprio 1 for the second-dispatched wave half (waves 4-7) over the attention prompt loop
# speedup vs baseline: 1.0007x; 1.0007x over previous
; #define GRAB(dst) do { if (tid == 0) *nl = (int)__hip_atomic_fetch_add(qctr, 1u, __ATOMIC_RELAXED, __HIP_MEMORY_SCOPE_AGENT); __syncthreads(); dst = __builtin_amdgcn_readfirstlane(*nl); __syncthreads(); } while (0)
; __global__ void __launch_bounds__(512, 2) fox_fwd(Args args) {
;     ...
;             fox::Seam S; unsigned* qctr = (unsigned*)(ws + WS_QUEUE); const float* QN = (const float*)(ws + WS_QN); const float* KN = (const float*)(ws + WS_KN);
;             int* nl = (int*)((char*)lds + fox::LDS_BIAS - 32);
;             auto mkref = [&](int n) { const int bh = n & 31, qb = 31 - (n >> 5), b = bh >> 3, h = bh & 7;
;                 fox::BlockRef r; r.K = Kb + (size_t)bh * SEQ * HD; r.O = MIX + ((size_t)b * SEQ + (size_t)qb * 256) * DM + h * HD; r.C = Cp + (size_t)bh * SEQ; r.P0 = qb * 256;
;                 r.nrm = 1.02f * fox::SCALE * sqrtf(QN[bh * 32 + qb] * KN[bh]); return r; };
;     ...
;             int n; GRAB(n);
;             if (n < NB * NH * 32) {
;                 fox::BlockRef cur = mkref(n);
;                 fox::prime(cur, (char*)lds, S);
;                 for (;;) {
;                     int nn; GRAB(nn); const bool last = nn >= NB * NH * 32;
;                     const fox::BlockRef nxt = last ? cur : mkref(nn);
;                     fox::block(cur, nxt, (char*)lds, S);
.Lp5_prompt:
	v_readfirstlane_b32 s98, v182
	s_nop 3
	s_lshr_b32 s98, s98, 6
	s_cmp_ge_u32 s98, 4
	s_cbranch_scc0 .Lp5_prio_done
	s_setprio 1

; __global__ void __launch_bounds__(512, 2) fox_fwd(Args args) {
;     ...
;         __syncthreads();
;     }
.Lp5_done:
	s_mov_b32 s99, 0
	s_setprio 0
	s_barrier
